# sc1 (L1-bypass) on the 16 GEMM1a loop LDS-DMA loads, on top of h1pf
# speedup vs baseline: 1.0090x; 1.0090x over previous
.LBB0_101:
	ds_read_b128 v[142:145], v161
	ds_read_b128 v[146:149], v234
	ds_read_b128 v[150:153], v161 offset:2048
	ds_read_b128 v[154:157], v234 offset:2048
	ds_read_b128 v[164:167], v162
	ds_read_b128 v[168:171], v235
	ds_read_b128 v[172:175], v162 offset:2048
	ds_read_b128 v[176:179], v235 offset:2048
	s_add_u32 s48, s46, 0xfff00080
	s_addc_u32 s49, s47, -1
	s_cmp_eq_u32 s77, 60
	s_cselect_b32 s51, s5, s49
	s_cselect_b32 s50, s29, s48
	s_cselect_b32 s49, s27, s76
	s_cselect_b32 s48, s74, s75
	v_lshl_add_u64 v[214:215], s[46:47], 0, v[134:135]
	s_add_i32 m0, s19, 0xc000
	ds_read_b128 v[180:183], v163
	ds_read_b128 v[184:187], v232
	ds_read_b128 v[188:191], v163 offset:2048
	ds_read_b128 v[192:195], v232 offset:2048
	ds_read_b128 v[196:199], v163 offset:4096
	ds_read_b128 v[200:203], v232 offset:4096
	ds_read_b128 v[204:207], v163 offset:6144
	ds_read_b128 v[208:211], v232 offset:6144
	global_load_lds_dwordx4 v[214:215], off sc1
	v_lshl_add_u64 v[214:215], s[46:47], 0, v[136:137]
	s_add_i32 m0, s19, 0xe000
	s_nop 0
	global_load_lds_dwordx4 v[214:215], off sc1
	s_waitcnt vmcnt(8)
	s_waitcnt lgkmcnt(0)
	s_barrier
	s_setprio 1
	s_waitcnt lgkmcnt(0)
	v_mfma_f32_16x16x32_bf16 v[124:127], v[142:145], v[180:183], v[124:127]
	v_mfma_f32_16x16x32_bf16 v[120:123], v[150:153], v[180:183], v[120:123]
	v_mfma_f32_16x16x32_bf16 v[116:119], v[142:145], v[188:191], v[116:119]
	v_mfma_f32_16x16x32_bf16 v[112:115], v[150:153], v[188:191], v[112:115]
	v_mfma_f32_16x16x32_bf16 v[100:103], v[142:145], v[196:199], v[100:103]
	v_mfma_f32_16x16x32_bf16 v[96:99], v[150:153], v[196:199], v[96:99]
	v_mfma_f32_16x16x32_bf16 v[84:87], v[142:145], v[204:207], v[84:87]
	v_mfma_f32_16x16x32_bf16 v[80:83], v[150:153], v[204:207], v[80:83]
	v_mfma_f32_16x16x32_bf16 v[124:127], v[146:149], v[184:187], v[124:127]
	v_mfma_f32_16x16x32_bf16 v[120:123], v[154:157], v[184:187], v[120:123]
	v_mfma_f32_16x16x32_bf16 v[116:119], v[146:149], v[192:195], v[116:119]
	v_mfma_f32_16x16x32_bf16 v[112:115], v[154:157], v[192:195], v[112:115]
	v_mfma_f32_16x16x32_bf16 v[100:103], v[146:149], v[200:203], v[100:103]
	v_mfma_f32_16x16x32_bf16 v[96:99], v[154:157], v[200:203], v[96:99]
	v_mfma_f32_16x16x32_bf16 v[84:87], v[146:149], v[208:211], v[84:87]
	v_mfma_f32_16x16x32_bf16 v[80:83], v[154:157], v[208:211], v[80:83]
	s_setprio 0
	s_setprio 1
	v_mfma_f32_16x16x32_bf16 v[108:111], v[164:167], v[180:183], v[108:111]
	v_mfma_f32_16x16x32_bf16 v[104:107], v[172:175], v[180:183], v[104:107]
	v_mfma_f32_16x16x32_bf16 v[92:95], v[164:167], v[188:191], v[92:95]
	v_mfma_f32_16x16x32_bf16 v[88:91], v[172:175], v[188:191], v[88:91]
	v_mfma_f32_16x16x32_bf16 v[76:79], v[164:167], v[196:199], v[76:79]
	v_mfma_f32_16x16x32_bf16 v[72:75], v[172:175], v[196:199], v[72:75]
	v_mfma_f32_16x16x32_bf16 v[68:71], v[164:167], v[204:207], v[68:71]
	v_mfma_f32_16x16x32_bf16 v[64:67], v[172:175], v[204:207], v[64:67]
	v_mfma_f32_16x16x32_bf16 v[108:111], v[168:171], v[184:187], v[108:111]
	v_mfma_f32_16x16x32_bf16 v[104:107], v[176:179], v[184:187], v[104:107]
	v_mfma_f32_16x16x32_bf16 v[92:95], v[168:171], v[192:195], v[92:95]
	v_mfma_f32_16x16x32_bf16 v[88:91], v[176:179], v[192:195], v[88:91]
	v_mfma_f32_16x16x32_bf16 v[76:79], v[168:171], v[200:203], v[76:79]
	v_mfma_f32_16x16x32_bf16 v[72:75], v[176:179], v[200:203], v[72:75]
	v_mfma_f32_16x16x32_bf16 v[68:71], v[168:171], v[208:211], v[68:71]
	v_mfma_f32_16x16x32_bf16 v[64:67], v[176:179], v[208:211], v[64:67]
	s_setprio 0
	s_barrier
	s_add_i32 s78, s68, s58
	v_lshl_add_u64 v[214:215], s[48:49], 0, v[128:129]
	s_mov_b32 m0, s78
	ds_read_b128 v[180:183], v163 offset:16384
	ds_read_b128 v[184:187], v232 offset:16384
	ds_read_b128 v[188:191], v163 offset:18432
	ds_read_b128 v[192:195], v232 offset:18432
	ds_read_b128 v[196:199], v163 offset:20480
	ds_read_b128 v[200:203], v232 offset:20480
	ds_read_b128 v[204:207], v163 offset:22528
	ds_read_b128 v[208:211], v232 offset:22528
	global_load_lds_dwordx4 v[214:215], off sc1
	s_add_i32 m0, s78, 0x2000
	s_add_u32 s78, s48, 0x100000
	v_lshl_add_u64 v[216:217], s[48:49], 0, v[130:131]
	s_addc_u32 s79, s49, 0
	s_add_i32 s80, s69, s58
	global_load_lds_dwordx4 v[216:217], off sc1
	v_lshl_add_u64 v[218:219], s[78:79], 0, v[128:129]
	s_mov_b32 m0, s80
	v_lshl_add_u64 v[220:221], s[50:51], 0, v[130:131]
	global_load_lds_dwordx4 v[218:219], off sc1
	v_lshl_add_u64 v[218:219], s[78:79], 0, v[130:131]
	s_add_i32 m0, s80, 0x2000
	s_nop 0
	global_load_lds_dwordx4 v[218:219], off sc1
	v_lshl_add_u64 v[218:219], s[50:51], 0, v[128:129]
	s_mov_b32 m0, s19
	s_nop 0
	global_load_lds_dwordx4 v[218:219], off sc1
	s_mov_b32 m0, s59
	s_nop 0
	global_load_lds_dwordx4 v[220:221], off sc1
	s_waitcnt vmcnt(8)
	s_waitcnt lgkmcnt(0)
	s_barrier
	s_setprio 1
	s_waitcnt lgkmcnt(0)
	v_mfma_f32_16x16x32_bf16 v[60:63], v[142:145], v[180:183], v[60:63]
	v_mfma_f32_16x16x32_bf16 v[56:59], v[150:153], v[180:183], v[56:59]
	v_mfma_f32_16x16x32_bf16 v[52:55], v[142:145], v[188:191], v[52:55]
	v_mfma_f32_16x16x32_bf16 v[48:51], v[150:153], v[188:191], v[48:51]
	v_mfma_f32_16x16x32_bf16 v[36:39], v[142:145], v[196:199], v[36:39]
	v_mfma_f32_16x16x32_bf16 v[32:35], v[150:153], v[196:199], v[32:35]
	v_mfma_f32_16x16x32_bf16 v[20:23], v[142:145], v[204:207], v[20:23]
	v_mfma_f32_16x16x32_bf16 v[16:19], v[150:153], v[204:207], v[16:19]
	v_mfma_f32_16x16x32_bf16 v[60:63], v[146:149], v[184:187], v[60:63]
	v_mfma_f32_16x16x32_bf16 v[56:59], v[154:157], v[184:187], v[56:59]
	v_mfma_f32_16x16x32_bf16 v[52:55], v[146:149], v[192:195], v[52:55]
	v_mfma_f32_16x16x32_bf16 v[48:51], v[154:157], v[192:195], v[48:51]
	v_mfma_f32_16x16x32_bf16 v[36:39], v[146:149], v[200:203], v[36:39]
	v_mfma_f32_16x16x32_bf16 v[32:35], v[154:157], v[200:203], v[32:35]
	v_mfma_f32_16x16x32_bf16 v[20:23], v[146:149], v[208:211], v[20:23]
	v_mfma_f32_16x16x32_bf16 v[16:19], v[154:157], v[208:211], v[16:19]
	s_setprio 0
	s_setprio 1
	v_mfma_f32_16x16x32_bf16 v[44:47], v[164:167], v[180:183], v[44:47]
	v_mfma_f32_16x16x32_bf16 v[40:43], v[172:175], v[180:183], v[40:43]
	v_mfma_f32_16x16x32_bf16 v[28:31], v[164:167], v[188:191], v[28:31]
	v_mfma_f32_16x16x32_bf16 v[24:27], v[172:175], v[188:191], v[24:27]
	v_mfma_f32_16x16x32_bf16 v[12:15], v[164:167], v[196:199], v[12:15]
	v_mfma_f32_16x16x32_bf16 v[8:11], v[172:175], v[196:199], v[8:11]
	v_mfma_f32_16x16x32_bf16 v[4:7], v[164:167], v[204:207], v[4:7]
	v_mfma_f32_16x16x32_bf16 v[0:3], v[172:175], v[204:207], v[0:3]
	v_mfma_f32_16x16x32_bf16 v[44:47], v[168:171], v[184:187], v[44:47]
	v_mfma_f32_16x16x32_bf16 v[40:43], v[176:179], v[184:187], v[40:43]
	v_mfma_f32_16x16x32_bf16 v[28:31], v[168:171], v[192:195], v[28:31]
	v_mfma_f32_16x16x32_bf16 v[24:27], v[176:179], v[192:195], v[24:27]
	v_mfma_f32_16x16x32_bf16 v[12:15], v[168:171], v[200:203], v[12:15]
	v_mfma_f32_16x16x32_bf16 v[8:11], v[176:179], v[200:203], v[8:11]
	v_mfma_f32_16x16x32_bf16 v[4:7], v[168:171], v[208:211], v[4:7]
	v_mfma_f32_16x16x32_bf16 v[0:3], v[176:179], v[208:211], v[0:3]
	s_setprio 0
	s_barrier
	s_add_i32 s78, 0, 0x18000
	s_add_i32 s79, 0, 0x1c000
	v_add_u32_e32 v154, s78, v160
	v_add_u32_e32 v230, s78, v233
	v_add_u32_e32 v176, s79, v160
	v_add_u32_e32 v231, s79, v233
	ds_read_b128 v[142:145], v154
	ds_read_b128 v[146:149], v230
	ds_read_b128 v[150:153], v154 offset:2048
	ds_read_b128 v[154:157], v230 offset:2048
	ds_read_b128 v[164:167], v176
	ds_read_b128 v[168:171], v231
	ds_read_b128 v[172:175], v176 offset:2048
	ds_read_b128 v[176:179], v231 offset:2048
	s_add_u32 s50, s50, 0x100000
	s_addc_u32 s51, s51, 0
	s_mov_b32 m0, s60
	v_lshl_add_u64 v[222:223], s[50:51], 0, v[128:129]
	ds_read_b128 v[180:183], v163 offset:32768
	ds_read_b128 v[184:187], v232 offset:32768
	ds_read_b128 v[188:191], v163 offset:34816
	ds_read_b128 v[192:195], v232 offset:34816
	ds_read_b128 v[196:199], v163 offset:36864
	ds_read_b128 v[200:203], v232 offset:36864
	ds_read_b128 v[204:207], v163 offset:38912
	ds_read_b128 v[208:211], v232 offset:38912
	global_load_lds_dwordx4 v[222:223], off sc1
	v_lshl_add_u64 v[222:223], s[50:51], 0, v[130:131]
	s_mov_b32 m0, s61
	s_nop 0
	global_load_lds_dwordx4 v[222:223], off sc1
	s_waitcnt vmcnt(8)
	s_waitcnt lgkmcnt(0)
	s_barrier
	s_setprio 1
	s_waitcnt lgkmcnt(0)
	v_mfma_f32_16x16x32_bf16 v[124:127], v[142:145], v[180:183], v[124:127]
	v_mfma_f32_16x16x32_bf16 v[120:123], v[150:153], v[180:183], v[120:123]
	v_mfma_f32_16x16x32_bf16 v[116:119], v[142:145], v[188:191], v[116:119]
	v_mfma_f32_16x16x32_bf16 v[112:115], v[150:153], v[188:191], v[112:115]
	v_mfma_f32_16x16x32_bf16 v[100:103], v[142:145], v[196:199], v[100:103]
	v_mfma_f32_16x16x32_bf16 v[96:99], v[150:153], v[196:199], v[96:99]
	v_mfma_f32_16x16x32_bf16 v[84:87], v[142:145], v[204:207], v[84:87]
	v_mfma_f32_16x16x32_bf16 v[80:83], v[150:153], v[204:207], v[80:83]
	v_mfma_f32_16x16x32_bf16 v[124:127], v[146:149], v[184:187], v[124:127]
	v_mfma_f32_16x16x32_bf16 v[120:123], v[154:157], v[184:187], v[120:123]
	v_mfma_f32_16x16x32_bf16 v[116:119], v[146:149], v[192:195], v[116:119]
	v_mfma_f32_16x16x32_bf16 v[112:115], v[154:157], v[192:195], v[112:115]
	v_mfma_f32_16x16x32_bf16 v[100:103], v[146:149], v[200:203], v[100:103]
	v_mfma_f32_16x16x32_bf16 v[96:99], v[154:157], v[200:203], v[96:99]
	v_mfma_f32_16x16x32_bf16 v[84:87], v[146:149], v[208:211], v[84:87]
	v_mfma_f32_16x16x32_bf16 v[80:83], v[154:157], v[208:211], v[80:83]
	s_setprio 0
	s_setprio 1
	v_mfma_f32_16x16x32_bf16 v[108:111], v[164:167], v[180:183], v[108:111]
	v_mfma_f32_16x16x32_bf16 v[104:107], v[172:175], v[180:183], v[104:107]
	v_mfma_f32_16x16x32_bf16 v[92:95], v[164:167], v[188:191], v[92:95]
	v_mfma_f32_16x16x32_bf16 v[88:91], v[172:175], v[188:191], v[88:91]
	v_mfma_f32_16x16x32_bf16 v[76:79], v[164:167], v[196:199], v[76:79]
	v_mfma_f32_16x16x32_bf16 v[72:75], v[172:175], v[196:199], v[72:75]
	v_mfma_f32_16x16x32_bf16 v[68:71], v[164:167], v[204:207], v[68:71]
	v_mfma_f32_16x16x32_bf16 v[64:67], v[172:175], v[204:207], v[64:67]
	v_mfma_f32_16x16x32_bf16 v[108:111], v[168:171], v[184:187], v[108:111]
	v_mfma_f32_16x16x32_bf16 v[104:107], v[176:179], v[184:187], v[104:107]
	v_mfma_f32_16x16x32_bf16 v[92:95], v[168:171], v[192:195], v[92:95]
	v_mfma_f32_16x16x32_bf16 v[88:91], v[176:179], v[192:195], v[88:91]
	v_mfma_f32_16x16x32_bf16 v[76:79], v[168:171], v[200:203], v[76:79]
	v_mfma_f32_16x16x32_bf16 v[72:75], v[176:179], v[200:203], v[72:75]
	v_mfma_f32_16x16x32_bf16 v[68:71], v[168:171], v[208:211], v[68:71]
	v_mfma_f32_16x16x32_bf16 v[64:67], v[176:179], v[208:211], v[64:67]
	s_setprio 0
	s_barrier
; template <class Epi, class Sched, bool FP8 = false>
; __device__ __forceinline__ void gemm_phase(LAS unsigned char* lds, const Gemm g, const Sched& S, const Epi& E, const int tid) {
;     ...
;         for (int t = 0; t < nt; t += 2) PG8_KBODY(t);
	s_add_i32 s50, s78, s58
	v_lshl_add_u64 v[214:215], v[214:215], 0, s[14:15]
	s_mov_b32 m0, s50
	ds_read_b128 v[180:183], v163 offset:49152
	ds_read_b128 v[184:187], v232 offset:49152
	ds_read_b128 v[188:191], v163 offset:51200
	ds_read_b128 v[192:195], v232 offset:51200
	ds_read_b128 v[196:199], v163 offset:53248
	ds_read_b128 v[200:203], v232 offset:53248
	ds_read_b128 v[204:207], v163 offset:55296
	ds_read_b128 v[208:211], v232 offset:55296
	global_load_lds_dwordx4 v[214:215], off sc1
	s_add_i32 m0, s50, 0x2000
	s_add_u32 s48, s48, 0x100080
	v_lshl_add_u64 v[214:215], v[216:217], 0, s[14:15]
	s_addc_u32 s49, s49, 0
	s_add_i32 s50, s79, s58
	global_load_lds_dwordx4 v[214:215], off sc1
	v_lshl_add_u64 v[214:215], s[48:49], 0, v[128:129]
	s_mov_b32 m0, s50
	s_nop 0
	global_load_lds_dwordx4 v[214:215], off sc1
	v_lshl_add_u64 v[214:215], s[48:49], 0, v[130:131]
	s_add_i32 m0, s50, 0x2000
	s_nop 0
	global_load_lds_dwordx4 v[214:215], off sc1
	v_lshl_add_u64 v[214:215], v[218:219], 0, s[14:15]
	s_mov_b32 m0, s66
	s_nop 0
	global_load_lds_dwordx4 v[214:215], off sc1
	v_lshl_add_u64 v[214:215], v[220:221], 0, s[14:15]
	s_mov_b32 m0, s67
	s_nop 0
	global_load_lds_dwordx4 v[214:215], off sc1
	s_waitcnt vmcnt(8)
	s_waitcnt lgkmcnt(0)
	s_barrier
	s_setprio 1
	s_waitcnt lgkmcnt(0)
	v_mfma_f32_16x16x32_bf16 v[60:63], v[142:145], v[180:183], v[60:63]
	v_mfma_f32_16x16x32_bf16 v[56:59], v[150:153], v[180:183], v[56:59]
	v_mfma_f32_16x16x32_bf16 v[52:55], v[142:145], v[188:191], v[52:55]
	v_mfma_f32_16x16x32_bf16 v[48:51], v[150:153], v[188:191], v[48:51]
	v_mfma_f32_16x16x32_bf16 v[36:39], v[142:145], v[196:199], v[36:39]
	v_mfma_f32_16x16x32_bf16 v[32:35], v[150:153], v[196:199], v[32:35]
	v_mfma_f32_16x16x32_bf16 v[20:23], v[142:145], v[204:207], v[20:23]
	v_mfma_f32_16x16x32_bf16 v[16:19], v[150:153], v[204:207], v[16:19]
	v_mfma_f32_16x16x32_bf16 v[60:63], v[146:149], v[184:187], v[60:63]
	v_mfma_f32_16x16x32_bf16 v[56:59], v[154:157], v[184:187], v[56:59]
	v_mfma_f32_16x16x32_bf16 v[52:55], v[146:149], v[192:195], v[52:55]
	v_mfma_f32_16x16x32_bf16 v[48:51], v[154:157], v[192:195], v[48:51]
	v_mfma_f32_16x16x32_bf16 v[36:39], v[146:149], v[200:203], v[36:39]
	v_mfma_f32_16x16x32_bf16 v[32:35], v[154:157], v[200:203], v[32:35]
	v_mfma_f32_16x16x32_bf16 v[20:23], v[146:149], v[208:211], v[20:23]
	v_mfma_f32_16x16x32_bf16 v[16:19], v[154:157], v[208:211], v[16:19]
	s_setprio 0
	s_setprio 1
	v_mfma_f32_16x16x32_bf16 v[44:47], v[164:167], v[180:183], v[44:47]
	v_mfma_f32_16x16x32_bf16 v[40:43], v[172:175], v[180:183], v[40:43]
	v_mfma_f32_16x16x32_bf16 v[28:31], v[164:167], v[188:191], v[28:31]
	v_mfma_f32_16x16x32_bf16 v[24:27], v[172:175], v[188:191], v[24:27]
	v_mfma_f32_16x16x32_bf16 v[12:15], v[164:167], v[196:199], v[12:15]
	v_mfma_f32_16x16x32_bf16 v[8:11], v[172:175], v[196:199], v[8:11]
	v_mfma_f32_16x16x32_bf16 v[4:7], v[164:167], v[204:207], v[4:7]
	v_mfma_f32_16x16x32_bf16 v[0:3], v[172:175], v[204:207], v[0:3]
	v_mfma_f32_16x16x32_bf16 v[44:47], v[168:171], v[184:187], v[44:47]
	v_mfma_f32_16x16x32_bf16 v[40:43], v[176:179], v[184:187], v[40:43]
	v_mfma_f32_16x16x32_bf16 v[28:31], v[168:171], v[192:195], v[28:31]
	v_mfma_f32_16x16x32_bf16 v[24:27], v[176:179], v[192:195], v[24:27]
	v_mfma_f32_16x16x32_bf16 v[12:15], v[168:171], v[200:203], v[12:15]
	v_mfma_f32_16x16x32_bf16 v[8:11], v[176:179], v[200:203], v[8:11]
	v_mfma_f32_16x16x32_bf16 v[4:7], v[168:171], v[208:211], v[4:7]
	v_mfma_f32_16x16x32_bf16 v[0:3], v[176:179], v[208:211], v[0:3]
	s_setprio 0
	s_barrier
	s_add_i32 s77, s77, 2
	s_add_u32 s46, s46, 0x100
	s_addc_u32 s47, s47, 0
	s_add_u32 s75, s75, 0x100
	s_addc_u32 s76, s76, 0
	s_cmp_gt_u32 s77, 61
	s_cbranch_scc0 .LBB0_101
	s_and_b64 vcc, exec, s[16:17]
	s_cbranch_vccz .LBB0_104
	s_barrier
